# speedup vs baseline: 1.0051x; 1.0051x over previous
; __device__ __forceinline__ float ex2(float x) { return __builtin_amdgcn_exp2f(x); }
; __device__ void attn_c_item(const Params& p, int layer, int b, int hq, int qblk, unsigned char* smem) {
;     ...
;     bf16_t* mix = reinterpret_cast<bf16_t*>(p.ws + WS_MIX);
;     float* sqc = reinterpret_cast<float*>(p.ws + WS_YC) + ((size_t)layer * 2 + 1) * T;
;     const float* gsw = reinterpret_cast<const float*>(p.ws + WS_LAM) + SM_SWA + layer * 512 + hq * 64;
; #pragma unroll
;     for (int qt = 0; qt < 2; ++qt) {
;         const float l0 = ls[qt][0] + ex2(sink2 - ub[qt]);
;         const float i0 = 1.f / l0;
;         const size_t tok = (size_t)b * SEQ + qw0 + qt * 16 + l15;
;         float ss = 0.f;
; #pragma unroll
;         for (int et = 0; et < 4; ++et) {
;             const float4 gg = *reinterpret_cast<const float4*>(gsw + et * 16 + kg * 4);
;             const float y0 = o[qt][et][0] * i0, y1 = o[qt][et][1] * i0, y2 = o[qt][et][2] * i0, y3 = o[qt][et][3] * i0;
;             ss += y0 * y0 + y1 * y1 + y2 * y2 + y3 * y3;
;             u32x2 ov = {pk2(y0 * gg.x, y1 * gg.y), pk2(y2 * gg.z, y3 * gg.w)};
;             *reinterpret_cast<u32x2*>(mix + tok * D + 512 + hq * 64 + et * 16 + kg * 4) = ov;
;         }
;         ss += __shfl_xor(ss, 16); ss += __shfl_xor(ss, 32);
;         if (kg == 0) atomicAdd(sqc + tok, ss);
;     }
.LBB0_404:
	s_or_b64 exec, exec, s[4:5]
	s_lshl_b32 s2, s11, 6
	s_lshl_b32 s62, s10, 14
	s_lshl_b32 s3, s2, 2
	v_readlane_b32 s4, v254, 59
	s_add_u32 s4, s4, s3
	v_readlane_b32 s3, v254, 60
	s_addc_u32 s5, s3, 0
	v_sub_f32_e32 v4, v104, v108
	v_exp_f32_e32 v12, v4
	global_load_dwordx4 v[136:139], v0, s[4:5]
	global_load_dwordx4 v[140:143], v0, s[4:5] offset:64
	global_load_dwordx4 v[144:147], v0, s[4:5] offset:128
	global_load_dwordx4 v[148:151], v0, s[4:5] offset:192
	v_ashrrev_i32_e32 v101, 31, v100
	v_lshl_add_u64 v[2:3], s[62:63], 0, v[100:101]
	v_add_f32_e32 v14, v12, v54
	s_lshl_b32 s62, s2, 1
	v_div_scale_f32 v15, s[2:3], v14, v14, 1.0
	v_rcp_f32_e32 v17, v15
	v_div_scale_f32 v16, vcc, 1.0, v14, 1.0
	v_or_b32_e32 v2, v2, v103
	v_fma_f32 v39, -v15, v17, 1.0
	v_fmac_f32_e32 v17, v39, v17
	v_mul_f32_e32 v39, v16, v17
	v_fma_f32 v40, -v15, v39, v16
	v_fmac_f32_e32 v39, v40, v17
	v_lshlrev_b64 v[4:5], 11, v[2:3]
	v_fma_f32 v15, -v15, v39, v16
	v_lshl_add_u64 v[10:11], s[58:59], 0, v[4:5]
	v_div_fmas_f32 v15, v15, v17, v39
	v_mov_b32_e32 v99, v1
	v_lshl_add_u64 v[10:11], v[10:11], 0, s[62:63]
	v_div_fixup_f32 v14, v15, v14, 1.0
	v_lshl_add_u64 v[10:11], v[10:11], 0, v[98:99]
	v_pk_mul_f32 v[16:17], v[18:19], v[14:15] op_sel_hi:[1,0]
	v_pk_mul_f32 v[18:19], v[20:21], v[14:15] op_sel_hi:[1,0]
	v_add_co_u32_e64 v12, s[2:3], s65, v10
	v_pk_mul_f32 v[20:21], v[50:51], v[14:15] op_sel_hi:[1,0]
	s_nop 0
	v_addc_co_u32_e64 v13, s[2:3], 0, v11, s[2:3]
	v_pk_mul_f32 v[40:41], v[52:53], v[14:15] op_sel_hi:[1,0]
	s_mov_b64 s[2:3], 0x16400400
	v_pk_mul_f32 v[46:47], v[46:47], v[14:15] op_sel_hi:[1,0]
	v_pk_mul_f32 v[48:49], v[48:49], v[14:15] op_sel_hi:[1,0]
	v_pk_mul_f32 v[42:43], v[42:43], v[14:15] op_sel_hi:[1,0]
	v_pk_mul_f32 v[14:15], v[44:45], v[14:15] op_sel_hi:[1,0]
	v_pk_mul_f32 v[44:45], v[48:49], v[48:49]
	v_readlane_b32 s6, v254, 57
	v_readlane_b32 s7, v254, 58
	s_waitcnt vmcnt(0)
	v_pk_mul_f32 v[6:7], v[136:137], v[16:17]
	v_pk_mul_f32 v[8:9], v[18:19], v[138:139]
	v_cvt_pk_bf16_f32 v6, v6, v7
	v_cvt_pk_bf16_f32 v7, v8, v9
	global_store_dwordx2 v[12:13], v[6:7], off offset:1024
	v_lshl_add_u64 v[12:13], v[10:11], 0, s[2:3]
	v_cmp_eq_u32_e64 s[2:3], 0, v102
	v_lshl_add_u64 v[2:3], v[2:3], 2, s[6:7]
	v_pk_mul_f32 v[6:7], v[20:21], v[140:141]
	v_pk_mul_f32 v[8:9], v[40:41], v[142:143]
	v_cvt_pk_bf16_f32 v6, v6, v7
	v_cvt_pk_bf16_f32 v7, v8, v9
	global_store_dwordx2 v[12:13], v[6:7], off offset:32
	v_pk_mul_f32 v[6:7], v[46:47], v[144:145]
	v_pk_mul_f32 v[8:9], v[48:49], v[146:147]
	v_cvt_pk_bf16_f32 v6, v6, v7
	v_cvt_pk_bf16_f32 v7, v8, v9
	global_store_dwordx2 v[12:13], v[6:7], off offset:64
	v_pk_mul_f32 v[6:7], v[16:17], v[16:17]
	v_pk_mul_f32 v[16:17], v[18:19], v[18:19]
	v_pk_mul_f32 v[18:19], v[20:21], v[20:21]
	v_pk_mul_f32 v[20:21], v[40:41], v[40:41]
	v_pk_mul_f32 v[40:41], v[46:47], v[46:47]
	v_add_f32_e32 v18, v18, v19
	v_add_f32_e32 v6, v6, v7
	v_pk_mul_f32 v[46:47], v[42:43], v[42:43]
	v_add_f32_e32 v7, v40, v41
	v_add_f32_e32 v18, v20, v18
	v_add_f32_e32 v6, v16, v6
	v_pk_mul_f32 v[48:49], v[14:15], v[14:15]
	v_add_f32_e32 v19, v46, v47
	v_add_f32_e32 v7, v44, v7
	v_add_f32_e32 v18, v21, v18
	v_add_f32_e32 v6, v17, v6
	v_add_f32_e32 v16, v48, v19
	v_add_f32_e32 v7, v45, v7
	v_add_f32_e32 v6, v6, v18
	v_add_f32_e32 v16, v49, v16
	v_add_f32_e32 v6, v7, v6
	v_add_f32_e32 v6, v16, v6
	ds_bpermute_b32 v7, v105, v6
	s_waitcnt lgkmcnt(0)
	v_add_f32_e32 v6, v6, v7
	ds_bpermute_b32 v7, v106, v6
	v_pk_mul_f32 v[8:9], v[42:43], v[148:149]
	v_pk_mul_f32 v[10:11], v[14:15], v[150:151]
	v_cvt_pk_bf16_f32 v8, v8, v9
	v_cvt_pk_bf16_f32 v9, v10, v11
	global_store_dwordx2 v[12:13], v[8:9], off offset:96
	s_and_saveexec_b64 s[6:7], s[2:3]
	s_cbranch_execz .LBB0_406
	s_waitcnt lgkmcnt(0)
	v_add_f32_e32 v6, v6, v7
	global_atomic_add_f32 v[2:3], v6, off
.LBB0_406:
	s_or_b64 exec, exec, s[6:7]
	v_lshl_add_u64 v[10:11], s[4:5], 0, v[0:1]
	s_waitcnt lgkmcnt(0)
	v_sub_f32_e32 v12, v104, v107
	v_exp_f32_e32 v14, v12
	v_or_b32_e32 v4, 0x8000, v4
	v_lshlrev_b32_e32 v0, 2, v102
	v_lshl_add_u64 v[4:5], s[58:59], 0, v[4:5]
	v_lshlrev_b32_e32 v0, 1, v0
	v_lshl_add_u64 v[4:5], v[4:5], 0, s[62:63]
	v_lshl_add_u64 v[12:13], v[4:5], 0, v[0:1]
	v_add_f32_e32 v0, v14, v38
	v_div_scale_f32 v14, s[4:5], v0, v0, 1.0
	v_rcp_f32_e32 v15, v14
	v_add_co_u32_e32 v4, vcc, s65, v12
	s_mov_b64 s[4:5], 0x16400400
	s_nop 0
	v_addc_co_u32_e32 v5, vcc, 0, v13, vcc
	v_fma_f32 v17, -v14, v15, 1.0
	v_div_scale_f32 v16, vcc, 1.0, v0, 1.0
	v_fmac_f32_e32 v15, v17, v15
	v_mul_f32_e32 v17, v16, v15
	v_fma_f32 v18, -v14, v17, v16
	v_fmac_f32_e32 v17, v18, v15
	v_fma_f32 v14, -v14, v17, v16
	v_div_fmas_f32 v14, v14, v15, v17
	v_div_fixup_f32 v0, v14, v0, 1.0
	v_pk_mul_f32 v[14:15], v[0:1], v[34:35] op_sel_hi:[0,1]
	v_pk_mul_f32 v[16:17], v[0:1], v[36:37] op_sel_hi:[0,1]
	v_pk_mul_f32 v[18:19], v[0:1], v[30:31] op_sel_hi:[0,1]
	v_pk_mul_f32 v[20:21], v[0:1], v[32:33] op_sel_hi:[0,1]
	v_lshl_add_u64 v[12:13], v[12:13], 0, s[4:5]
	v_pk_mul_f32 v[26:27], v[0:1], v[26:27] op_sel_hi:[0,1]
	v_pk_mul_f32 v[28:29], v[0:1], v[28:29] op_sel_hi:[0,1]
	v_pk_mul_f32 v[6:7], v[14:15], v[136:137]
	v_pk_mul_f32 v[8:9], v[16:17], v[138:139]
	v_cvt_pk_bf16_f32 v6, v6, v7
	v_cvt_pk_bf16_f32 v7, v8, v9
	global_store_dwordx2 v[4:5], v[6:7], off offset:1024
	v_pk_mul_f32 v[4:5], v[18:19], v[140:141]
	v_pk_mul_f32 v[6:7], v[20:21], v[142:143]
	v_cvt_pk_bf16_f32 v4, v4, v5
	v_cvt_pk_bf16_f32 v5, v6, v7
	global_store_dwordx2 v[12:13], v[4:5], off offset:32
	v_pk_mul_f32 v[4:5], v[26:27], v[144:145]
	v_pk_mul_f32 v[6:7], v[28:29], v[146:147]
	v_cvt_pk_bf16_f32 v4, v4, v5
	v_cvt_pk_bf16_f32 v5, v6, v7
	global_store_dwordx2 v[12:13], v[4:5], off offset:64
	v_pk_mul_f32 v[4:5], v[14:15], v[14:15]
	v_pk_mul_f32 v[14:15], v[16:17], v[16:17]
	v_pk_mul_f32 v[16:17], v[18:19], v[18:19]
	v_pk_mul_f32 v[10:11], v[0:1], v[22:23] op_sel_hi:[0,1]
	v_pk_mul_f32 v[22:23], v[0:1], v[24:25] op_sel_hi:[0,1]
	v_pk_mul_f32 v[18:19], v[20:21], v[20:21]
	v_pk_mul_f32 v[20:21], v[26:27], v[26:27]
	v_add_f32_e32 v0, v16, v17
	v_add_f32_e32 v4, v4, v5
	v_pk_mul_f32 v[24:25], v[28:29], v[28:29]
	v_pk_mul_f32 v[26:27], v[10:11], v[10:11]
	v_add_f32_e32 v5, v20, v21
	v_add_f32_e32 v0, v18, v0
	v_add_f32_e32 v4, v14, v4
	v_pk_mul_f32 v[28:29], v[22:23], v[22:23]
	v_add_f32_e32 v16, v26, v27
	v_add_f32_e32 v5, v24, v5
	v_add_f32_e32 v0, v19, v0
	v_add_f32_e32 v4, v15, v4
	v_add_f32_e32 v14, v28, v16
	v_add_f32_e32 v5, v25, v5
	v_add_f32_e32 v0, v4, v0
	v_add_f32_e32 v14, v29, v14
	v_add_f32_e32 v0, v0, v5
	v_add_f32_e32 v0, v0, v14
	ds_bpermute_b32 v4, v105, v0
	s_waitcnt lgkmcnt(0)
	v_add_f32_e32 v0, v0, v4
	ds_bpermute_b32 v4, v106, v0
	v_pk_mul_f32 v[6:7], v[10:11], v[148:149]
	v_pk_mul_f32 v[8:9], v[22:23], v[150:151]
	v_cvt_pk_bf16_f32 v6, v6, v7
	v_cvt_pk_bf16_f32 v7, v8, v9
	global_store_dwordx2 v[12:13], v[6:7], off offset:96
	s_and_saveexec_b64 s[4:5], s[2:3]
	s_cbranch_execz .LBB0_408
	s_waitcnt lgkmcnt(0)
	v_add_f32_e32 v0, v0, v4
	global_atomic_add_f32 v[2:3], v0, off offset:64

; __device__ void attn_b_item(const Params& p, int layer, int b, int h, int qblk, unsigned char* smem) {
;     ...
;     bf16_t* mix = reinterpret_cast<bf16_t*>(p.ws + WS_MIX);
;     float* sqb = reinterpret_cast<float*>(p.ws + WS_YC) + ((size_t)layer * 2 + 0) * T;
;     const float* gsb = reinterpret_cast<const float*>(p.ws + WS_LAM) + SM_SB + layer * 256 + h * 64;
; #pragma unroll
;     for (int qt = 0; qt < 2; ++qt) {
;         const size_t tok = (size_t)b * SEQ + qw0 + qt * 16 + l15;
;         float ss = 0.f;
; #pragma unroll
;         for (int et = 0; et < 4; ++et) {
;             const float4 gg = *reinterpret_cast<const float4*>(gsb + et * 16 + kg * 4);
;             const float y0 = o[qt][et][0], y1 = o[qt][et][1], y2 = o[qt][et][2], y3 = o[qt][et][3];
;             ss += y0 * y0 + y1 * y1 + y2 * y2 + y3 * y3;
;             u32x2 ov = {pk2(y0 * gg.x, y1 * gg.y), pk2(y2 * gg.z, y3 * gg.w)};
;             *reinterpret_cast<u32x2*>(mix + tok * D + 256 + h * 64 + et * 16 + kg * 4) = ov;
;         }
;         ss += __shfl_xor(ss, 16); ss += __shfl_xor(ss, 32);
;         if (kg == 0) atomicAdd(sqb + tok, ss);
;     }
.LBB0_425:
	s_lshl_b32 s62, s30, 14
	s_lshl_b32 s2, s29, 2
	v_readlane_b32 s3, v254, 63
	s_add_u32 s4, s3, s2
	v_readlane_b32 s2, v255, 0
	s_addc_u32 s5, s2, 0
	global_load_dwordx4 v[136:139], v92, s[4:5]
	global_load_dwordx4 v[140:143], v92, s[4:5] offset:64
	global_load_dwordx4 v[144:147], v92, s[4:5] offset:128
	global_load_dwordx4 v[148:151], v92, s[4:5] offset:192
	v_ashrrev_i32_e32 v95, 31, v94
	v_lshl_add_u64 v[2:3], s[62:63], 0, v[94:95]
	v_or_b32_e32 v2, v2, v117
	v_lshlrev_b64 v[36:37], 11, v[2:3]
	s_lshl_b32 s62, s29, 1
	v_lshl_add_u64 v[42:43], s[58:59], 0, v[36:37]
	v_mov_b32_e32 v97, v1
	v_lshl_add_u64 v[42:43], v[42:43], 0, s[62:63]
	v_lshl_add_u64 v[42:43], v[42:43], 0, v[96:97]
	v_add_co_u32_e32 v44, vcc, s65, v42
	s_mov_b64 s[2:3], 0x16400200
	s_nop 0
	v_addc_co_u32_e32 v45, vcc, 0, v43, vcc
	v_lshl_add_u64 v[42:43], v[42:43], 0, s[2:3]
	v_xor_b32_e32 v0, 16, v208
	v_mul_f32_e32 v46, v21, v21
	v_fmac_f32_e32 v46, v20, v20
	v_fmac_f32_e32 v46, v22, v22
	v_fmac_f32_e32 v46, v23, v23
	s_waitcnt vmcnt(0)
	v_pk_mul_f32 v[38:39], v[32:33], v[136:137]
	v_pk_mul_f32 v[40:41], v[34:35], v[138:139]
	v_cvt_pk_bf16_f32 v38, v38, v39
	v_cvt_pk_bf16_f32 v39, v40, v41
	global_store_dwordx2 v[44:45], v[38:39], off offset:512
	v_and_b32_e32 v44, 64, v208
	v_mul_f32_e32 v33, v33, v33
	v_add_u32_e32 v44, 64, v44
	v_fmac_f32_e32 v33, v32, v32
	v_cmp_lt_i32_e32 vcc, v0, v44
	v_fmac_f32_e32 v33, v34, v34
	v_fmac_f32_e32 v33, v35, v35
	v_cndmask_b32_e32 v0, v208, v0, vcc
	v_xor_b32_e32 v45, 32, v208
	v_cmp_lt_i32_e64 s[2:3], v45, v44
	v_cmp_eq_u32_e32 vcc, 0, v116
	v_pk_mul_f32 v[38:39], v[28:29], v[140:141]
	v_pk_mul_f32 v[40:41], v[30:31], v[142:143]
	v_cvt_pk_bf16_f32 v38, v38, v39
	v_cvt_pk_bf16_f32 v39, v40, v41
	global_store_dwordx2 v[42:43], v[38:39], off offset:32
	v_mul_f32_e32 v29, v29, v29
	v_fmac_f32_e32 v29, v28, v28
	v_fmac_f32_e32 v29, v30, v30
	v_fmac_f32_e32 v29, v31, v31
	v_pk_mul_f32 v[38:39], v[24:25], v[144:145]
	v_pk_mul_f32 v[40:41], v[26:27], v[146:147]
	v_cvt_pk_bf16_f32 v38, v38, v39
	v_cvt_pk_bf16_f32 v39, v40, v41
	global_store_dwordx2 v[42:43], v[38:39], off offset:64
	v_mul_f32_e32 v25, v25, v25
	v_fmac_f32_e32 v25, v24, v24
	v_fmac_f32_e32 v25, v26, v26
	v_lshlrev_b32_e32 v24, 2, v0
	v_fmac_f32_e32 v25, v27, v27
	v_add_f32_e32 v0, v29, v33
	v_add_f32_e32 v0, v25, v0
	v_add_f32_e32 v0, v46, v0
	ds_bpermute_b32 v26, v24, v0
	v_cndmask_b32_e64 v25, v208, v45, s[2:3]
	v_lshlrev_b32_e32 v25, 2, v25
	v_readlane_b32 s2, v254, 61
	v_readlane_b32 s3, v254, 62
	s_waitcnt lgkmcnt(0)
	v_add_f32_e32 v0, v0, v26
	ds_bpermute_b32 v26, v25, v0
	v_lshl_add_u64 v[2:3], v[2:3], 2, s[2:3]
	v_pk_mul_f32 v[20:21], v[20:21], v[148:149]
	v_pk_mul_f32 v[22:23], v[22:23], v[150:151]
	v_cvt_pk_bf16_f32 v20, v20, v21
	v_cvt_pk_bf16_f32 v21, v22, v23
	global_store_dwordx2 v[42:43], v[20:21], off offset:96
	s_and_saveexec_b64 s[2:3], vcc
	s_cbranch_execz .LBB0_427
	s_waitcnt lgkmcnt(0)
	v_add_f32_e32 v0, v0, v26
	global_atomic_add_f32 v[2:3], v0, off
.LBB0_427:
	s_or_b64 exec, exec, s[2:3]
	v_or_b32_e32 v36, 0x8000, v36
	v_lshlrev_b32_e32 v0, 2, v116
	v_mov_b32_e32 v93, v1
	v_lshl_add_u64 v[20:21], s[58:59], 0, v[36:37]
	s_waitcnt lgkmcnt(0)
	v_lshl_add_u64 v[26:27], s[4:5], 0, v[92:93]
	v_lshl_add_u64 v[20:21], v[20:21], 0, s[62:63]
	v_lshlrev_b32_e32 v0, 1, v0
	v_lshl_add_u64 v[28:29], v[20:21], 0, v[0:1]
	v_mul_f32_e32 v0, v17, v17
	v_fmac_f32_e32 v0, v16, v16
	v_fmac_f32_e32 v0, v18, v18
	s_mov_b64 s[2:3], 0x16400200
	v_fmac_f32_e32 v0, v19, v19
	v_lshl_add_u64 v[30:31], v[28:29], 0, s[2:3]
	v_pk_mul_f32 v[16:17], v[16:17], v[136:137]
	v_pk_mul_f32 v[18:19], v[18:19], v[138:139]
	v_cvt_pk_bf16_f32 v16, v16, v17
	v_cvt_pk_bf16_f32 v17, v18, v19
	v_add_co_u32_e64 v18, s[2:3], s65, v28
	s_nop 1
	v_addc_co_u32_e64 v19, s[2:3], 0, v29, s[2:3]
	global_store_dwordx2 v[18:19], v[16:17], off offset:512
	v_mul_f32_e32 v16, v13, v13
	v_fmac_f32_e32 v16, v12, v12
	v_fmac_f32_e32 v16, v14, v14
	v_fmac_f32_e32 v16, v15, v15
	v_add_f32_e32 v0, v16, v0
	v_pk_mul_f32 v[12:13], v[12:13], v[140:141]
	v_pk_mul_f32 v[14:15], v[14:15], v[142:143]
	v_cvt_pk_bf16_f32 v12, v12, v13
	v_cvt_pk_bf16_f32 v13, v14, v15
	global_store_dwordx2 v[30:31], v[12:13], off offset:32
	v_mul_f32_e32 v12, v9, v9
	v_fmac_f32_e32 v12, v8, v8
	v_fmac_f32_e32 v12, v10, v10
	v_fmac_f32_e32 v12, v11, v11
	v_add_f32_e32 v0, v12, v0
	v_pk_mul_f32 v[8:9], v[8:9], v[144:145]
	v_pk_mul_f32 v[10:11], v[10:11], v[146:147]
	v_cvt_pk_bf16_f32 v8, v8, v9
	v_cvt_pk_bf16_f32 v9, v10, v11
	global_store_dwordx2 v[30:31], v[8:9], off offset:64
	v_mul_f32_e32 v8, v5, v5
	v_fmac_f32_e32 v8, v4, v4
	v_fmac_f32_e32 v8, v6, v6
	v_fmac_f32_e32 v8, v7, v7
	v_add_f32_e32 v0, v8, v0
	v_pk_mul_f32 v[4:5], v[4:5], v[148:149]
	v_pk_mul_f32 v[6:7], v[6:7], v[150:151]
	v_cvt_pk_bf16_f32 v4, v4, v5
	v_cvt_pk_bf16_f32 v5, v6, v7
	global_store_dwordx2 v[30:31], v[4:5], off offset:96
	ds_bpermute_b32 v4, v24, v0
	s_waitcnt lgkmcnt(0)
	v_add_f32_e32 v0, v0, v4
	ds_bpermute_b32 v4, v25, v0
	s_and_saveexec_b64 s[2:3], vcc
	s_xor_b64 s[2:3], exec, s[2:3]
	s_cbranch_execz .LBB0_429
	s_waitcnt lgkmcnt(0)
	v_add_f32_e32 v0, v0, v4
	global_atomic_add_f32 v[2:3], v0, off offset:64
